# K-loops: flips removed, one static s_setprio 1 for waves 0..3 during each K-loop
# baseline (speedup 1.0000x reference)
.LBB0_314:
	s_add_u32 s71, s26, 0x100
	s_addc_u32 s72, s27, 0
	s_add_i32 s70, s69, 1
	s_lshl_b32 s0, s70, 2
	v_readlane_b32 s2, v253, 22
	s_add_i32 s0, s0, s2
	s_cmp_lt_i32 s0, 22
	s_cselect_b64 s[60:61], -1, 0
	s_cmp_gt_i32 s0, 21
	s_cselect_b64 s[56:57], -1, 0
	s_ashr_i32 s1, s0, 31
	s_lshl_b64 s[0:1], s[0:1], 19
	v_readlane_b32 s3, v253, 23
	s_add_u32 s2, s62, s0
	s_addc_u32 s3, s63, s1
	s_and_b64 s[0:1], s[60:61], exec
	s_cselect_b32 s27, s3, s27
	s_cselect_b32 s26, s2, s26
	s_cselect_b32 s59, s25, s35
	s_cselect_b32 s58, s24, s34
	s_add_u32 s0, s34, 0x40080
	s_addc_u32 s1, s35, 0
	v_lshl_add_u64 v[130:131], s[0:1], 0, v[180:181]
	v_lshl_add_u64 v[132:133], s[0:1], 0, v[178:179]
	s_mov_b32 s6, -2
	s_mov_b64 s[0:1], 0
	s_mov_b64 s[42:43], 0x80
	v_readfirstlane_b32 vcc_lo, v216
	s_nop 3
	s_lshr_b32 vcc_lo, vcc_lo, 6
	s_cmp_lt_u32 vcc_lo, 4
	s_cbranch_scc0 .Lprio_skip1
	s_setprio 1

.LBB0_349:
	s_mov_b32 s57, 2
	s_mov_b64 s[0:1], 0x100
	v_mov_b64_e32 v[2:3], v[206:207]
	v_mov_b64_e32 v[132:133], v[204:205]
	s_mov_b64 s[42:43], 0x80
	v_readfirstlane_b32 vcc_lo, v216
	s_nop 3
	s_lshr_b32 vcc_lo, vcc_lo, 6
	s_cmp_lt_u32 vcc_lo, 4
	s_cbranch_scc0 .Lprio_skip2
	s_setprio 1

.LBB0_571:
	s_cmp_lt_i32 s54, 1
	s_cbranch_scc1 .LBB0_574
	v_mad_u64_u32 v[132:133], s[0:1], s55, v185, v[184:185]
	v_readlane_b32 s0, v252, 39
	s_add_i32 s4, s54, -2
	v_readlane_b32 s1, v252, 40
	s_lshl_b32 s8, s55, 7
	s_mov_b32 s9, s1
	s_add_u32 s5, s28, 0x100
	v_mad_u64_u32 v[2:3], s[2:3], v213, s55, v[186:187]
	s_addc_u32 s6, s29, 0
	s_mov_b32 s3, s9
	s_add_u32 s0, s26, 0x80
	v_mov_b32_e32 v3, v1
	v_mov_b32_e32 v133, v1
	v_writelane_b32 v252, s2, 39
	s_addc_u32 s1, s27, 0
	v_lshl_add_u64 v[2:3], s[8:9], 0, v[2:3]
	v_writelane_b32 v252, s3, 40
	v_lshl_add_u64 v[132:133], s[8:9], 0, v[132:133]
	s_mov_b32 s2, 0
	v_readfirstlane_b32 vcc_lo, v216
	s_nop 3
	s_lshr_b32 vcc_lo, vcc_lo, 6
	s_cmp_lt_u32 vcc_lo, 4
	s_cbranch_scc0 .Lprio_skip3
	s_setprio 1

.LBB0_911:
	s_cmp_lt_i32 s44, 1
	s_cbranch_scc1 .LBB0_914
	v_mad_u64_u32 v[136:137], s[62:63], s17, v133, v[132:133]
	v_readlane_b32 s62, v252, 39
	s_add_i32 s10, s44, -2
	v_readlane_b32 s63, v252, 40
	s_lshl_b32 s66, s17, 7
	s_mov_b32 s67, s63
	s_add_u32 s11, s6, 0x100
	s_addc_u32 s15, s7, 0
	v_mad_u64_u32 v[2:3], s[64:65], v141, s17, v[134:135]
	s_mov_b32 s35, s67
	s_add_u32 s62, s4, 0x80
	v_mov_b32_e32 v3, v1
	v_mov_b32_e32 v137, v1
	v_writelane_b32 v252, s34, 39
	s_addc_u32 s63, s5, 0
	v_lshl_add_u64 v[2:3], s[66:67], 0, v[2:3]
	v_writelane_b32 v252, s35, 40
	v_lshl_add_u64 v[136:137], s[66:67], 0, v[136:137]
	s_mov_b32 s64, 0
	s_mov_b64 s[42:43], 0x80
	v_readfirstlane_b32 vcc_lo, v216
	s_nop 3
	s_lshr_b32 vcc_lo, vcc_lo, 6
	s_cmp_lt_u32 vcc_lo, 4
	s_cbranch_scc0 .Lprio_skip4
	s_setprio 1

.LBB0_1025:
	s_add_u32 s74, s0, 0x100
	s_addc_u32 s75, s1, 0
	s_add_u32 s0, s14, 0x40080
	s_addc_u32 s1, s15, 0
	v_lshl_add_u64 v[130:131], s[0:1], 0, v[146:147]
	v_lshl_add_u64 v[132:133], s[0:1], 0, v[144:145]
	s_mov_b32 s6, -2
	s_mov_b64 s[0:1], 0
	s_mov_b64 s[42:43], 0x80
	v_readfirstlane_b32 vcc_lo, v216
	s_nop 3
	s_lshr_b32 vcc_lo, vcc_lo, 6
	s_cmp_lt_u32 vcc_lo, 4
	s_cbranch_scc0 .Lprio_skip0
	s_setprio 1
